# v25 + dilated-attention unit loop: the per-unit vmcnt(0) store drain moved to the loop pre-header so store acks overlap the next unit's loads
# speedup vs baseline: 1.0140x; 1.0006x over previous
; __device__ __forceinline__ int bid_opaque() { int b = blockIdx.x; asm volatile("" : "+s"(b)); return b; }
; __global__ void __launch_bounds__(512, 2) mega_fwd(Args a) {
;     ...
;  { const bool g0 = (kind == K_COMBINE); const int nu = a.nc * 8 * (g0 ? 16 : 32);
;    const int b_ = bid_opaque(), G_ = gridDim.x; const int vcu = (G_ % 8 == 0) ? (b_ % 8) * (G_ / 8) + b_ / 8 : b_;
;    for (int u = vcu; u < nu; u += G_) dil_attn_unit(lds, PROJ, LSE, nu - 1 - u, Tc, g0 ? HY : (bf16_t*)nullptr); }
.LBB0_246:
	s_cmp_lg_u32 s87, 3
	s_cselect_b64 s[88:89], -1, 0
	s_cmp_eq_u32 s87, 3
	s_cselect_b64 s[0:1], -1, 0
	s_and_b64 s[4:5], s[0:1], exec
	s_cselect_b32 s3, 4, 5
	v_readlane_b32 s4, v254, 53
	s_lshl_b32 s86, s4, s3
	s_cmp_ge_i32 s2, s86
	s_cbranch_scc1 .LBB0_268
	s_not_b32 s63, s2
	s_xor_b64 s[90:91], s[0:1], -1
	s_waitcnt vmcnt(0)
	s_branch .LBB0_250

; __device__ __forceinline__ int tid_opaque() { int t = threadIdx.x; asm volatile("" : "+v"(t)); return t; }
; __device__ __forceinline__ void dil_attn_unit(LAS unsigned char* lds, bf16_t* proj, float* lse, int unit, int Tc, bf16_t* ybuf) {
;     const int tid = tid_opaque(), lane = tid & 63, w = __builtin_amdgcn_readfirstlane(tid >> 6), r32 = lane & 31, hi = lane >> 5;
;     const int sh = ybuf ? (unit >> 4) : (unit >> 5), sub = ybuf ? (unit & 15) : 16 + (unit & 31); const int s = sh >> 3, h = sh & 7;
;     int g, r, blk; if (sub < 16) { g = 0; r = 0; blk = sub; } else if (sub < 32) { g = 1; r = (sub - 16) >> 2; blk = (sub - 16) & 3; } else { g = 2; r = sub - 32; blk = 0; }
.LBB0_250:
	v_mov_b32_e32 v189, v176
	v_cndmask_b32_e64 v0, 0, 1, s[88:89]
	v_cmp_ne_u32_e64 s[4:5], 1, v0
	s_andn2_b64 vcc, exec, s[88:89]
	v_readfirstlane_b32 s6, v189
	s_cbranch_vccnz .LBB0_255
	s_and_b32 s7, s63, 31
	s_cmp_gt_u32 s7, 15
	s_mov_b64 s[0:1], -1
	s_cbranch_scc0 .LBB0_253
	s_add_i32 s76, s7, -16
	s_mov_b64 s[0:1], 0
